# v12 with static priority 1 for waves 4-7 during the GEMM phases and no per-segment s_setprio flips in the K-loop
# speedup vs baseline: 1.0016x; 1.0016x over previous
.LBB0_21:
	s_setprio 0
	s_nop 0
	v_writelane_b32 v255, s46, 23
	v_readlane_b32 s0, v253, 48
	s_add_i32 s0, s0, 1
	v_writelane_b32 v255, s47, 24
	v_writelane_b32 v255, s48, 18
	v_writelane_b32 v253, s0, 48
	v_writelane_b32 v255, s49, 19
	v_readlane_b32 s77, v254, 24
	v_readlane_b32 s0, v253, 49
	v_readlane_b32 s12, v254, 3
	v_writelane_b32 v255, s54, 20
	s_add_i32 s77, s77, 1
	s_add_i32 s0, s0, 1
	v_readlane_b32 s13, v254, 4
	v_writelane_b32 v255, s24, 21
	v_readlane_b32 s14, v254, 1
	v_readlane_b32 s18, v254, 6
	v_readlane_b32 s20, v254, 8
	v_readlane_b32 s22, v254, 10
	v_readlane_b32 s24, v254, 12
	s_mov_b32 s70, 0xfffe0000
	v_writelane_b32 v253, s0, 49
	s_cmp_ge_i32 s77, s13
	v_writelane_b32 v255, s16, 22
	v_readlane_b32 s15, v254, 2
	v_readlane_b32 s16, v254, 5
	v_readlane_b32 s19, v254, 7
	v_readlane_b32 s21, v254, 9
	v_readlane_b32 s23, v254, 11
	v_readlane_b32 s25, v254, 13
	v_readlane_b32 s33, v254, 14
	v_readlane_b32 s68, v254, 15
	s_movk_i32 s71, 0x3ff
	s_movk_i32 s69, 0x2000
	s_movk_i32 s72, 0x7ff
	s_movk_i32 s73, 0x1fff
	s_movk_i32 s74, 0x1000
	s_movk_i32 s75, 0x2400
	s_mov_b32 s76, 0xf800000
	s_cbranch_scc1 .LBB0_529

.LBB0_269:
	s_and_b64 vcc, exec, s[20:21]
	s_cbranch_vccnz .Lsp_lo
	s_setprio 1

.LBB0_270:
	v_add_u32_e32 v140, 0x10000, v223
	v_add_u32_e32 v156, 0x14000, v223
	s_waitcnt lgkmcnt(0)
	ds_read_b128 v[128:131], v140
	ds_read_b128 v[132:135], v140 offset:1024
	ds_read_b128 v[136:139], v140 offset:2048
	ds_read_b128 v[140:143], v140 offset:3072
	ds_read_b128 v[144:147], v156
	ds_read_b128 v[148:151], v156 offset:1024
	ds_read_b128 v[152:155], v156 offset:2048
	ds_read_b128 v[182:185], v156 offset:3072
	s_add_i32 s44, s3, 0x80
	s_cmp_eq_u32 s100, s43
	s_cselect_b32 s45, s25, s44
	s_cselect_b32 s90, s2, s42
	s_add_i32 s44, s45, 0x80
	s_add_i32 s48, s73, s3
	s_mov_b32 s76, s46
	s_mov_b32 m0, s96
	ds_read_b128 v[186:189], v224
	ds_read_b128 v[190:193], v224 offset:1024
	ds_read_b128 v[232:235], v224 offset:2048
	ds_read_b128 v[236:239], v224 offset:3072
	ds_read_b128 v[240:243], v224 offset:4096
	ds_read_b128 v[244:247], v224 offset:5120
	ds_read_b128 v[248:251], v224 offset:6144
	ds_read_b128 v[202:205], v224 offset:7168
	buffer_load_dwordx4 v217, s[76:79], s48 offen lds
	s_mov_b32 m0, s97
	s_nop 0
	buffer_load_dwordx4 v219, s[76:79], s48 offen lds
	s_waitcnt vmcnt(8)
	s_waitcnt lgkmcnt(0)
	s_barrier
	s_waitcnt lgkmcnt(7)
	v_mfma_f32_16x16x32_bf16 v[124:127], v[128:131], v[186:189], v[124:127]
	v_mfma_f32_16x16x32_bf16 v[120:123], v[136:139], v[186:189], v[120:123]
	s_waitcnt lgkmcnt(5)
	v_mfma_f32_16x16x32_bf16 v[108:111], v[128:131], v[232:235], v[108:111]
	v_mfma_f32_16x16x32_bf16 v[104:107], v[136:139], v[232:235], v[104:107]
	s_waitcnt lgkmcnt(3)
	v_mfma_f32_16x16x32_bf16 v[92:95], v[128:131], v[240:243], v[92:95]
	v_mfma_f32_16x16x32_bf16 v[88:91], v[136:139], v[240:243], v[88:91]
	s_waitcnt lgkmcnt(1)
	v_mfma_f32_16x16x32_bf16 v[76:79], v[128:131], v[248:251], v[76:79]
	v_mfma_f32_16x16x32_bf16 v[72:75], v[136:139], v[248:251], v[72:75]
	v_mfma_f32_16x16x32_bf16 v[124:127], v[132:135], v[190:193], v[124:127]
	v_mfma_f32_16x16x32_bf16 v[120:123], v[140:143], v[190:193], v[120:123]
	v_mfma_f32_16x16x32_bf16 v[108:111], v[132:135], v[236:239], v[108:111]
	v_mfma_f32_16x16x32_bf16 v[104:107], v[140:143], v[236:239], v[104:107]
	v_mfma_f32_16x16x32_bf16 v[92:95], v[132:135], v[244:247], v[92:95]
	v_mfma_f32_16x16x32_bf16 v[88:91], v[140:143], v[244:247], v[88:91]
	s_waitcnt lgkmcnt(0)
	v_mfma_f32_16x16x32_bf16 v[76:79], v[132:135], v[202:205], v[76:79]
	v_mfma_f32_16x16x32_bf16 v[72:75], v[140:143], v[202:205], v[72:75]
	v_mfma_f32_16x16x32_bf16 v[116:119], v[144:147], v[186:189], v[116:119]
	v_mfma_f32_16x16x32_bf16 v[112:115], v[152:155], v[186:189], v[112:115]
	v_mfma_f32_16x16x32_bf16 v[100:103], v[144:147], v[232:235], v[100:103]
	v_mfma_f32_16x16x32_bf16 v[96:99], v[152:155], v[232:235], v[96:99]
	v_mfma_f32_16x16x32_bf16 v[84:87], v[144:147], v[240:243], v[84:87]
	v_mfma_f32_16x16x32_bf16 v[80:83], v[152:155], v[240:243], v[80:83]
	v_mfma_f32_16x16x32_bf16 v[68:71], v[144:147], v[248:251], v[68:71]
	v_mfma_f32_16x16x32_bf16 v[64:67], v[152:155], v[248:251], v[64:67]
	v_mfma_f32_16x16x32_bf16 v[116:119], v[148:151], v[190:193], v[116:119]
	v_mfma_f32_16x16x32_bf16 v[112:115], v[182:185], v[190:193], v[112:115]
	v_mfma_f32_16x16x32_bf16 v[100:103], v[148:151], v[236:239], v[100:103]
	v_mfma_f32_16x16x32_bf16 v[96:99], v[182:185], v[236:239], v[96:99]
	v_mfma_f32_16x16x32_bf16 v[84:87], v[148:151], v[244:247], v[84:87]
	v_mfma_f32_16x16x32_bf16 v[80:83], v[182:185], v[244:247], v[80:83]
	v_mfma_f32_16x16x32_bf16 v[68:71], v[148:151], v[202:205], v[68:71]
	v_mfma_f32_16x16x32_bf16 v[64:67], v[182:185], v[202:205], v[64:67]
	s_barrier
	s_mov_b32 m0, s71
	s_mov_b32 s48, s94
	s_mov_b32 s50, s78
	s_mov_b32 s51, s79
	ds_read_b128 v[186:189], v224 offset:16384
	ds_read_b128 v[190:193], v224 offset:17408
	ds_read_b128 v[202:205], v224 offset:18432
	ds_read_b128 v[232:235], v224 offset:19456
	ds_read_b128 v[236:239], v224 offset:20480
	ds_read_b128 v[240:243], v224 offset:21504
	ds_read_b128 v[244:247], v224 offset:22528
	ds_read_b128 v[248:251], v224 offset:23552
	buffer_load_dwordx4 v218, s[48:51], s90 offen lds
	s_mov_b32 m0, s28
	s_add_i32 s91, s90, s64
	buffer_load_dwordx4 v220, s[48:51], s90 offen lds
	s_mov_b32 m0, s29
	s_nop 0
	buffer_load_dwordx4 v218, s[48:51], s91 offen lds
	s_mov_b32 m0, s26
	s_nop 0
	buffer_load_dwordx4 v220, s[48:51], s91 offen lds
	s_mov_b32 m0, s70
	s_nop 0
	buffer_load_dwordx4 v217, s[76:79], s45 offen lds
	s_mov_b32 m0, s27
	s_nop 0
	buffer_load_dwordx4 v219, s[76:79], s45 offen lds
	s_waitcnt vmcnt(8)
	s_waitcnt lgkmcnt(0)
	s_barrier
	s_waitcnt lgkmcnt(7)
	v_mfma_f32_16x16x32_bf16 v[60:63], v[128:131], v[186:189], v[60:63]
	v_mfma_f32_16x16x32_bf16 v[56:59], v[136:139], v[186:189], v[56:59]
	s_waitcnt lgkmcnt(5)
	v_mfma_f32_16x16x32_bf16 v[44:47], v[128:131], v[202:205], v[44:47]
	v_mfma_f32_16x16x32_bf16 v[40:43], v[136:139], v[202:205], v[40:43]
	s_waitcnt lgkmcnt(3)
	v_mfma_f32_16x16x32_bf16 v[28:31], v[128:131], v[236:239], v[28:31]
	v_mfma_f32_16x16x32_bf16 v[24:27], v[136:139], v[236:239], v[24:27]
	s_waitcnt lgkmcnt(1)
	v_mfma_f32_16x16x32_bf16 v[12:15], v[128:131], v[244:247], v[12:15]
	v_mfma_f32_16x16x32_bf16 v[8:11], v[136:139], v[244:247], v[8:11]
	v_mfma_f32_16x16x32_bf16 v[60:63], v[132:135], v[190:193], v[60:63]
	v_mfma_f32_16x16x32_bf16 v[56:59], v[140:143], v[190:193], v[56:59]
	v_mfma_f32_16x16x32_bf16 v[44:47], v[132:135], v[232:235], v[44:47]
	v_mfma_f32_16x16x32_bf16 v[40:43], v[140:143], v[232:235], v[40:43]
	v_mfma_f32_16x16x32_bf16 v[28:31], v[132:135], v[240:243], v[28:31]
	v_mfma_f32_16x16x32_bf16 v[24:27], v[140:143], v[240:243], v[24:27]
	s_waitcnt lgkmcnt(0)
	v_mfma_f32_16x16x32_bf16 v[12:15], v[132:135], v[248:251], v[12:15]
	v_mfma_f32_16x16x32_bf16 v[8:11], v[140:143], v[248:251], v[8:11]
	v_mfma_f32_16x16x32_bf16 v[52:55], v[144:147], v[186:189], v[52:55]
	v_mfma_f32_16x16x32_bf16 v[48:51], v[152:155], v[186:189], v[48:51]
	v_mfma_f32_16x16x32_bf16 v[36:39], v[144:147], v[202:205], v[36:39]
	v_mfma_f32_16x16x32_bf16 v[32:35], v[152:155], v[202:205], v[32:35]
	v_mfma_f32_16x16x32_bf16 v[20:23], v[144:147], v[236:239], v[20:23]
	v_mfma_f32_16x16x32_bf16 v[16:19], v[152:155], v[236:239], v[16:19]
	v_mfma_f32_16x16x32_bf16 v[4:7], v[144:147], v[244:247], v[4:7]
	v_mfma_f32_16x16x32_bf16 v[0:3], v[152:155], v[244:247], v[0:3]
	v_mfma_f32_16x16x32_bf16 v[52:55], v[148:151], v[190:193], v[52:55]
	v_mfma_f32_16x16x32_bf16 v[48:51], v[182:185], v[190:193], v[48:51]
	v_mfma_f32_16x16x32_bf16 v[36:39], v[148:151], v[232:235], v[36:39]
	v_mfma_f32_16x16x32_bf16 v[32:35], v[182:185], v[232:235], v[32:35]
	v_mfma_f32_16x16x32_bf16 v[20:23], v[148:151], v[240:243], v[20:23]
	v_mfma_f32_16x16x32_bf16 v[16:19], v[182:185], v[240:243], v[16:19]
	v_mfma_f32_16x16x32_bf16 v[4:7], v[148:151], v[248:251], v[4:7]
	v_mfma_f32_16x16x32_bf16 v[0:3], v[182:185], v[248:251], v[0:3]
	s_barrier
	v_add_u32_e32 v140, 0x18000, v223
	v_add_u32_e32 v156, 0x1c000, v223
	ds_read_b128 v[128:131], v140
	ds_read_b128 v[132:135], v140 offset:1024
	ds_read_b128 v[136:139], v140 offset:2048
	ds_read_b128 v[140:143], v140 offset:3072
	ds_read_b128 v[144:147], v156
	ds_read_b128 v[148:151], v156 offset:1024
	ds_read_b128 v[152:155], v156 offset:2048
	ds_read_b128 v[182:185], v156 offset:3072
	s_add_i32 s45, s45, s73
	s_mov_b32 m0, s62
	ds_read_b128 v[186:189], v224 offset:32768
	ds_read_b128 v[190:193], v224 offset:33792
	ds_read_b128 v[202:205], v224 offset:34816
	ds_read_b128 v[232:235], v224 offset:35840
	ds_read_b128 v[236:239], v224 offset:36864
	ds_read_b128 v[240:243], v224 offset:37888
	ds_read_b128 v[244:247], v224 offset:38912
	ds_read_b128 v[248:251], v224 offset:39936
	buffer_load_dwordx4 v217, s[76:79], s45 offen lds
	s_mov_b32 m0, s63
	s_nop 0
	buffer_load_dwordx4 v219, s[76:79], s45 offen lds
	s_waitcnt vmcnt(8)
	s_waitcnt lgkmcnt(0)
	s_barrier
	s_waitcnt lgkmcnt(7)
	v_mfma_f32_16x16x32_bf16 v[124:127], v[128:131], v[186:189], v[124:127]
	v_mfma_f32_16x16x32_bf16 v[120:123], v[136:139], v[186:189], v[120:123]
	s_waitcnt lgkmcnt(5)
	v_mfma_f32_16x16x32_bf16 v[108:111], v[128:131], v[202:205], v[108:111]
	v_mfma_f32_16x16x32_bf16 v[104:107], v[136:139], v[202:205], v[104:107]
	s_waitcnt lgkmcnt(3)
	v_mfma_f32_16x16x32_bf16 v[92:95], v[128:131], v[236:239], v[92:95]
	v_mfma_f32_16x16x32_bf16 v[88:91], v[136:139], v[236:239], v[88:91]
	s_waitcnt lgkmcnt(1)
	v_mfma_f32_16x16x32_bf16 v[76:79], v[128:131], v[244:247], v[76:79]
	v_mfma_f32_16x16x32_bf16 v[72:75], v[136:139], v[244:247], v[72:75]
	v_mfma_f32_16x16x32_bf16 v[124:127], v[132:135], v[190:193], v[124:127]
	v_mfma_f32_16x16x32_bf16 v[120:123], v[140:143], v[190:193], v[120:123]
	v_mfma_f32_16x16x32_bf16 v[108:111], v[132:135], v[232:235], v[108:111]
	v_mfma_f32_16x16x32_bf16 v[104:107], v[140:143], v[232:235], v[104:107]
	v_mfma_f32_16x16x32_bf16 v[92:95], v[132:135], v[240:243], v[92:95]
	v_mfma_f32_16x16x32_bf16 v[88:91], v[140:143], v[240:243], v[88:91]
	s_waitcnt lgkmcnt(0)
	v_mfma_f32_16x16x32_bf16 v[76:79], v[132:135], v[248:251], v[76:79]
	v_mfma_f32_16x16x32_bf16 v[72:75], v[140:143], v[248:251], v[72:75]
	v_mfma_f32_16x16x32_bf16 v[116:119], v[144:147], v[186:189], v[116:119]
	v_mfma_f32_16x16x32_bf16 v[112:115], v[152:155], v[186:189], v[112:115]
	v_mfma_f32_16x16x32_bf16 v[100:103], v[144:147], v[202:205], v[100:103]
	v_mfma_f32_16x16x32_bf16 v[96:99], v[152:155], v[202:205], v[96:99]
	v_mfma_f32_16x16x32_bf16 v[84:87], v[144:147], v[236:239], v[84:87]
	v_mfma_f32_16x16x32_bf16 v[80:83], v[152:155], v[236:239], v[80:83]
	v_mfma_f32_16x16x32_bf16 v[68:71], v[144:147], v[244:247], v[68:71]
	v_mfma_f32_16x16x32_bf16 v[64:67], v[152:155], v[244:247], v[64:67]
	v_mfma_f32_16x16x32_bf16 v[116:119], v[148:151], v[190:193], v[116:119]
	v_mfma_f32_16x16x32_bf16 v[112:115], v[182:185], v[190:193], v[112:115]
	v_mfma_f32_16x16x32_bf16 v[100:103], v[148:151], v[232:235], v[100:103]
	v_mfma_f32_16x16x32_bf16 v[96:99], v[182:185], v[232:235], v[96:99]
	v_mfma_f32_16x16x32_bf16 v[84:87], v[148:151], v[240:243], v[84:87]
	v_mfma_f32_16x16x32_bf16 v[80:83], v[182:185], v[240:243], v[80:83]
	v_mfma_f32_16x16x32_bf16 v[68:71], v[148:151], v[248:251], v[68:71]
	v_mfma_f32_16x16x32_bf16 v[64:67], v[182:185], v[248:251], v[64:67]
	s_barrier
	s_mov_b32 m0, s88
	s_add_i32 s45, s90, 0x80
	ds_read_b128 v[186:189], v224 offset:49152
	ds_read_b128 v[190:193], v224 offset:50176
	ds_read_b128 v[202:205], v224 offset:51200
	ds_read_b128 v[232:235], v224 offset:52224
	ds_read_b128 v[236:239], v224 offset:53248
	ds_read_b128 v[240:243], v224 offset:54272
	ds_read_b128 v[244:247], v224 offset:55296
	ds_read_b128 v[248:251], v224 offset:56320
	buffer_load_dwordx4 v218, s[48:51], s45 offen lds
	s_mov_b32 m0, s82
	s_nop 0
	buffer_load_dwordx4 v220, s[48:51], s45 offen lds
	s_add_i32 s45, s45, s64
	s_mov_b32 m0, s58
	s_nop 0
	buffer_load_dwordx4 v218, s[48:51], s45 offen lds
	s_mov_b32 m0, s59
	s_nop 0
	buffer_load_dwordx4 v220, s[48:51], s45 offen lds
	s_mov_b32 m0, s83
	s_nop 0
	buffer_load_dwordx4 v217, s[76:79], s44 offen lds
	s_mov_b32 m0, s89
	s_nop 0
	buffer_load_dwordx4 v219, s[76:79], s44 offen lds
	s_waitcnt vmcnt(8)
	s_waitcnt lgkmcnt(0)
	s_barrier
	s_waitcnt lgkmcnt(7)
	v_mfma_f32_16x16x32_bf16 v[60:63], v[128:131], v[186:189], v[60:63]
	v_mfma_f32_16x16x32_bf16 v[56:59], v[136:139], v[186:189], v[56:59]
	s_waitcnt lgkmcnt(5)
	v_mfma_f32_16x16x32_bf16 v[44:47], v[128:131], v[202:205], v[44:47]
	v_mfma_f32_16x16x32_bf16 v[40:43], v[136:139], v[202:205], v[40:43]
	s_waitcnt lgkmcnt(3)
	v_mfma_f32_16x16x32_bf16 v[28:31], v[128:131], v[236:239], v[28:31]
	v_mfma_f32_16x16x32_bf16 v[24:27], v[136:139], v[236:239], v[24:27]
	s_waitcnt lgkmcnt(1)
	v_mfma_f32_16x16x32_bf16 v[12:15], v[128:131], v[244:247], v[12:15]
	v_mfma_f32_16x16x32_bf16 v[8:11], v[136:139], v[244:247], v[8:11]
	v_mfma_f32_16x16x32_bf16 v[60:63], v[132:135], v[190:193], v[60:63]
	v_mfma_f32_16x16x32_bf16 v[56:59], v[140:143], v[190:193], v[56:59]
	v_mfma_f32_16x16x32_bf16 v[44:47], v[132:135], v[232:235], v[44:47]
	v_mfma_f32_16x16x32_bf16 v[40:43], v[140:143], v[232:235], v[40:43]
	v_mfma_f32_16x16x32_bf16 v[28:31], v[132:135], v[240:243], v[28:31]
	v_mfma_f32_16x16x32_bf16 v[24:27], v[140:143], v[240:243], v[24:27]
	s_waitcnt lgkmcnt(0)
	v_mfma_f32_16x16x32_bf16 v[12:15], v[132:135], v[248:251], v[12:15]
	v_mfma_f32_16x16x32_bf16 v[8:11], v[140:143], v[248:251], v[8:11]
	v_mfma_f32_16x16x32_bf16 v[52:55], v[144:147], v[186:189], v[52:55]
	v_mfma_f32_16x16x32_bf16 v[48:51], v[152:155], v[186:189], v[48:51]
	v_mfma_f32_16x16x32_bf16 v[36:39], v[144:147], v[202:205], v[36:39]
	v_mfma_f32_16x16x32_bf16 v[32:35], v[152:155], v[202:205], v[32:35]
	v_mfma_f32_16x16x32_bf16 v[20:23], v[144:147], v[236:239], v[20:23]
	v_mfma_f32_16x16x32_bf16 v[16:19], v[152:155], v[236:239], v[16:19]
	v_mfma_f32_16x16x32_bf16 v[4:7], v[144:147], v[244:247], v[4:7]
	v_mfma_f32_16x16x32_bf16 v[0:3], v[152:155], v[244:247], v[0:3]
	v_mfma_f32_16x16x32_bf16 v[52:55], v[148:151], v[190:193], v[52:55]
	v_mfma_f32_16x16x32_bf16 v[48:51], v[182:185], v[190:193], v[48:51]
	v_mfma_f32_16x16x32_bf16 v[36:39], v[148:151], v[232:235], v[36:39]
	v_mfma_f32_16x16x32_bf16 v[32:35], v[182:185], v[232:235], v[32:35]
	v_mfma_f32_16x16x32_bf16 v[20:23], v[148:151], v[240:243], v[20:23]
	v_mfma_f32_16x16x32_bf16 v[16:19], v[182:185], v[240:243], v[16:19]
	v_mfma_f32_16x16x32_bf16 v[4:7], v[148:151], v[248:251], v[4:7]
	v_mfma_f32_16x16x32_bf16 v[0:3], v[182:185], v[248:251], v[0:3]
	s_barrier
	s_add_i32 s43, s43, 2
	s_addk_i32 s3, 0x100
	s_addk_i32 s42, 0x100
	s_cmp_ge_i32 s43, s101
	s_cbranch_scc0 .LBB0_270
	s_and_b64 vcc, exec, s[20:21]
	s_cbranch_vccz .LBB0_273
	s_barrier
